# chunk-task W output: 32 two-byte stores per lane paired into 16 four-byte stores via a DPP neighbour swap + v_perm (plus packed d16_hi stores of the inverse blocks)
# speedup vs baseline: 1.0031x; 1.0031x over previous
.LBB0_758:
	v_mov_b32_e32 v0, s8
	v_mov_b32_e32 v1, s47
	v_cmp_lt_i32_e32 vcc, 3, v91
	s_add_i32 s10, s6, 0x100
	s_addk_i32 s6, 0x200
	v_cndmask_b32_e32 v0, v0, v1, vcc
	v_lshlrev_b32_e32 v1, 5, v91
	v_and_b32_e32 v78, 0x60, v1
	v_lshlrev_b32_e32 v1, 1, v78
	v_lshlrev_b32_e32 v2, 1, v95
	v_add3_u32 v16, v0, v1, v2
	v_mov_b32_e32 v0, s6
	v_mov_b32_e32 v1, s10
	v_cndmask_b32_e32 v0, v0, v1, vcc
	v_and_b32_e32 v1, 32, v10
	s_waitcnt lgkmcnt(0)
	s_barrier
	v_lshrrev_b32_e32 v97, 5, v10
	s_movk_i32 s6, 0x880
	v_add_u32_e32 v17, v0, v1
	v_mad_u32_u24 v14, v97, s6, v16
	ds_read_b128 v[0:3], v17
	ds_read_u16 v4, v14
	ds_read_u16 v5, v14 offset:272
	ds_read_u16 v10, v14 offset:816
	ds_read_u16 v11, v14 offset:1360
	ds_read_u16 v12, v14 offset:1904
	ds_read_u16 v13, v14 offset:4624
	ds_read_u16 v15, v14 offset:5168
	ds_read_u16 v18, v14 offset:5712
	v_lshlrev_b32_e32 v99, 3, v97
	s_waitcnt lgkmcnt(6)
	v_lshlrev_b32_e32 v9, 16, v5
	v_lshlrev_b32_e32 v8, 16, v4
	ds_read_b128 v[4:7], v17 offset:16
	v_pk_mul_f32 v[0:1], v[0:1], v[8:9]
	v_or_b32_e32 v8, 2, v99
	v_mad_u32_u24 v8, v8, s80, v16
	s_waitcnt lgkmcnt(6)
	v_lshlrev_b32_e32 v9, 16, v10
	ds_read_u16 v10, v8
	ds_read_u16 v19, v8 offset:544
	ds_read_u16 v20, v8 offset:1088
	ds_read_u16 v21, v8 offset:3808
	ds_read_u16 v22, v8 offset:4352
	ds_read_u16 v23, v8 offset:4896
	ds_read_u16 v24, v8 offset:5440
	s_waitcnt lgkmcnt(6)
	v_lshlrev_b32_e32 v8, 16, v10
	v_pk_mul_f32 v[2:3], v[2:3], v[8:9]
	v_lshlrev_b32_e32 v9, 16, v11
	s_waitcnt lgkmcnt(5)
	v_lshlrev_b32_e32 v8, 16, v19
	v_pk_mul_f32 v[4:5], v[4:5], v[8:9]
	v_lshlrev_b32_e32 v9, 16, v12
	s_waitcnt lgkmcnt(4)
	v_lshlrev_b32_e32 v8, 16, v20
	v_pk_mul_f32 v[8:9], v[6:7], v[8:9]
	v_cvt_pk_bf16_f32 v0, v0, v1
	v_cvt_pk_bf16_f32 v1, v2, v3
	v_cvt_pk_bf16_f32 v2, v4, v5
	ds_read_b128 v[4:7], v17 offset:64
	v_cvt_pk_bf16_f32 v3, v8, v9
	ds_read_b128 v[8:11], v17 offset:80
	v_lshlrev_b32_e32 v13, 16, v13
	s_waitcnt lgkmcnt(5)
	v_lshlrev_b32_e32 v12, 16, v21
	ds_read_u16 v14, v14 offset:6256
	s_waitcnt lgkmcnt(2)
	v_pk_mul_f32 v[4:5], v[4:5], v[12:13]
	v_lshlrev_b32_e32 v13, 16, v15
	v_lshlrev_b32_e32 v12, 16, v22
	v_pk_mul_f32 v[6:7], v[6:7], v[12:13]
	v_lshlrev_b32_e32 v13, 16, v18
	v_lshlrev_b32_e32 v12, 16, v23
	s_waitcnt lgkmcnt(1)
	v_pk_mul_f32 v[8:9], v[8:9], v[12:13]
	v_cvt_pk_bf16_f32 v4, v4, v5
	v_cvt_pk_bf16_f32 v5, v6, v7
	v_cvt_pk_bf16_f32 v6, v8, v9
	v_mov_b32_e32 v8, s95
	v_lshlrev_b32_e32 v98, 2, v97
	s_waitcnt lgkmcnt(0)
	v_lshlrev_b32_e32 v13, 16, v14
	v_lshlrev_b32_e32 v12, 16, v24
	v_mad_u32_u24 v100, v95, s93, v8
	v_lshlrev_b32_e32 v18, 4, v97
	v_or_b32_e32 v19, 32, v98
	v_pk_mul_f32 v[10:11], v[10:11], v[12:13]
	v_add_u32_e32 v12, v100, v18
	v_mad_u32_u24 v20, v19, s80, v16
	v_mad_u32_u24 v16, v97, s94, v16
	v_cvt_pk_bf16_f32 v7, v10, v11
	ds_read_b128 v[8:11], v12
	ds_read_b128 v[12:15], v12 offset:32
	v_sub_u32_e32 v26, v17, v18
	ds_read_u16 v17, v16 offset:8976
	ds_read_u16 v27, v16 offset:9520
	ds_read_u16 v28, v16 offset:11152
	ds_read_u16 v29, v16 offset:11696
	ds_read_u16 v30, v16 offset:13328
	ds_read_u16 v31, v16 offset:13872
	ds_read_u16 v83, v16 offset:15504
	ds_read_u16 v84, v16 offset:16048
	s_waitcnt lgkmcnt(7)
	v_lshlrev_b32_e32 v25, 16, v17
	ds_read_b128 v[16:19], v26 offset:128
	ds_read_u16 v21, v20
	ds_read_u16 v34, v20 offset:544
	ds_read_u16 v36, v20 offset:2176
	ds_read_u16 v38, v20 offset:2720
	ds_read_u16 v44, v20 offset:4352
	ds_read_u16 v80, v20 offset:4896
	ds_read_u16 v85, v20 offset:6528
	ds_read_u16 v86, v20 offset:7072
	s_waitcnt lgkmcnt(7)
	v_lshlrev_b32_e32 v24, 16, v21
	ds_read_b128 v[20:23], v26 offset:160
	ds_read_b128 v[40:43], v26 offset:192
	v_pk_mul_f32 v[32:33], v[16:17], v[24:25]
	v_lshlrev_b32_e32 v17, 16, v27
	s_waitcnt lgkmcnt(8)
	v_lshlrev_b32_e32 v16, 16, v34
	v_pk_mul_f32 v[34:35], v[18:19], v[16:17]
	v_lshlrev_b32_e32 v17, 16, v28
	s_waitcnt lgkmcnt(7)
	v_lshlrev_b32_e32 v16, 16, v36
	s_waitcnt lgkmcnt(1)
	v_pk_mul_f32 v[36:37], v[20:21], v[16:17]
	v_lshlrev_b32_e32 v17, 16, v29
	v_lshlrev_b32_e32 v16, 16, v38
	v_pk_mul_f32 v[38:39], v[22:23], v[16:17]
	v_lshlrev_b32_e32 v17, 16, v30
	v_lshlrev_b32_e32 v16, 16, v44
	ds_read_b128 v[44:47], v26 offset:224
	s_waitcnt lgkmcnt(1)
	v_pk_mul_f32 v[40:41], v[40:41], v[16:17]
	v_lshlrev_b32_e32 v81, 16, v31
	v_mfma_f32_32x32x16_bf16 v[16:31], v[8:11], v[0:3], 0
	v_mul_u32_u24_e32 v82, 0x50, v95
	v_lshlrev_b32_e32 v1, 16, v83
	v_lshlrev_b32_e32 v0, 16, v85
	v_add3_u32 v8, s96, v82, v99
	s_waitcnt lgkmcnt(0)
	v_pk_mul_f32 v[44:45], v[44:45], v[0:1]
	ds_read2_b64 v[0:3], v8 offset1:2
	v_lshlrev_b32_e32 v80, 16, v80
	v_mfma_f32_32x32x16_bf16 v[16:31], v[12:15], v[4:7], v[16:31]
	v_lshlrev_b32_e32 v5, 16, v84
	v_lshlrev_b32_e32 v4, 16, v86
	v_mul_f32_e64 v42, v42, v80
	v_mul_f32_e64 v43, v43, v81
	v_mul_f32_e64 v46, v46, v4
	v_mul_f32_e64 v47, v47, v5
	v_cmp_gt_i32_e32 vcc, 4, v91
	s_nop 4
	v_cvt_pk_bf16_f32 v80, v16, v17
	v_cvt_pk_bf16_f32 v81, v18, v19
	v_cvt_pk_bf16_f32 v82, v20, v21
	v_cvt_pk_bf16_f32 v83, v22, v23
	v_cvt_pk_bf16_f32 v84, v24, v25
	v_cvt_pk_bf16_f32 v85, v26, v27
	s_waitcnt lgkmcnt(0)
	v_mfma_f32_32x32x16_bf16 v[32:47], v[0:3], v[80:83], v[32:47]
	ds_read2_b64 v[0:3], v8 offset0:4 offset1:6
	v_cvt_pk_bf16_f32 v86, v28, v29
	v_cvt_pk_bf16_f32 v87, v30, v31
	s_waitcnt lgkmcnt(0)
	s_nop 0
	v_mfma_f32_32x32x16_bf16 v[32:47], v[0:3], v[84:87], v[32:47]
	v_add_u32_e32 v0, v100, v99
	v_add_u32_e32 v99, 0x800, v0
	ds_read2_b64 v[0:3], v99 offset0:64 offset1:66
	s_nop 8
	v_cvt_pk_bf16_f32 v4, v32, v33
	v_cvt_pk_bf16_f32 v5, v34, v35
	v_cvt_pk_bf16_f32 v6, v36, v37
	v_cvt_pk_bf16_f32 v7, v38, v39
	ds_read2_b64 v[32:35], v99 offset0:68 offset1:70
	v_cvt_pk_bf16_f32 v36, v40, v41
	s_waitcnt lgkmcnt(1)
	v_mfma_f32_32x32x16_bf16 v[0:15], v[0:3], v[4:7], 0
	v_cvt_pk_bf16_f32 v37, v42, v43
	v_cvt_pk_bf16_f32 v38, v44, v45
	v_cvt_pk_bf16_f32 v39, v46, v47
	s_waitcnt lgkmcnt(0)
	s_nop 0
	v_mfma_f32_32x32x16_bf16 v[0:15], v[32:35], v[36:39], v[0:15]
	v_or_b32_e32 v32, v78, v95
	s_and_saveexec_b64 s[10:11], vcc
	s_xor_b64 s[12:13], exec, s[10:11]
	s_cbranch_execz .LBB0_760
	s_ashr_i32 s59, s58, 31
	s_lshl_b64 s[10:11], s[58:59], 14
	s_add_u32 s10, s36, s10
	s_addc_u32 s11, s37, s11
	v_lshlrev_b32_e32 v78, 1, v32
	v_lshl_add_u64 v[32:33], s[10:11], 0, v[78:79]
	v_lshlrev_b32_e32 v78, 10, v97
	v_lshl_add_u64 v[32:33], v[32:33], 0, v[78:79]
	v_and_b32_e32 v86, 1, v95
	v_mov_b32_e32 v80, 0x1000504
	v_mov_b32_e32 v81, 0x7060302
	v_mov_b32_e32 v87, 0x1ffe
	v_mov_b32_e32 v83, 0
	v_cmp_eq_u32_e32 vcc, 1, v86
	s_mov_b64 s[98:99], 0x1000
	v_cvt_pk_bf16_f32 v16, -v16, -v0
	v_cvt_pk_bf16_f32 v17, -v17, -v1
	v_cvt_pk_bf16_f32 v18, -v18, -v2
	v_cvt_pk_bf16_f32 v19, -v19, -v3
	v_cvt_pk_bf16_f32 v20, -v20, -v4
	v_cvt_pk_bf16_f32 v21, -v21, -v5
	v_cvt_pk_bf16_f32 v22, -v22, -v6
	v_cvt_pk_bf16_f32 v23, -v23, -v7
	v_cvt_pk_bf16_f32 v24, -v24, -v8
	v_cvt_pk_bf16_f32 v25, -v25, -v9
	v_cvt_pk_bf16_f32 v26, -v26, -v10
	v_cvt_pk_bf16_f32 v27, -v27, -v11
	v_cvt_pk_bf16_f32 v28, -v28, -v12
	v_cvt_pk_bf16_f32 v29, -v29, -v13
	v_cvt_pk_bf16_f32 v30, -v30, -v14
	v_cvt_pk_bf16_f32 v31, -v31, -v15
	v_cndmask_b32_e32 v80, v80, v81, vcc
	v_cndmask_b32_e32 v82, 0, v87, vcc
	v_lshl_add_u64 v[82:83], v[82:83], 0, v[32:33]
	v_lshl_add_u64 v[84:85], v[82:83], 0, s[98:99]
	v_mov_b32_dpp v0, v16 quad_perm:[1,0,3,2] row_mask:0xf bank_mask:0xf
	v_mov_b32_dpp v1, v17 quad_perm:[1,0,3,2] row_mask:0xf bank_mask:0xf
	v_mov_b32_dpp v2, v18 quad_perm:[1,0,3,2] row_mask:0xf bank_mask:0xf
	v_mov_b32_dpp v3, v19 quad_perm:[1,0,3,2] row_mask:0xf bank_mask:0xf
	v_mov_b32_dpp v4, v20 quad_perm:[1,0,3,2] row_mask:0xf bank_mask:0xf
	v_mov_b32_dpp v5, v21 quad_perm:[1,0,3,2] row_mask:0xf bank_mask:0xf
	v_mov_b32_dpp v6, v22 quad_perm:[1,0,3,2] row_mask:0xf bank_mask:0xf
	v_mov_b32_dpp v7, v23 quad_perm:[1,0,3,2] row_mask:0xf bank_mask:0xf
	v_mov_b32_dpp v8, v24 quad_perm:[1,0,3,2] row_mask:0xf bank_mask:0xf
	v_mov_b32_dpp v9, v25 quad_perm:[1,0,3,2] row_mask:0xf bank_mask:0xf
	v_mov_b32_dpp v10, v26 quad_perm:[1,0,3,2] row_mask:0xf bank_mask:0xf
	v_mov_b32_dpp v11, v27 quad_perm:[1,0,3,2] row_mask:0xf bank_mask:0xf
	v_mov_b32_dpp v12, v28 quad_perm:[1,0,3,2] row_mask:0xf bank_mask:0xf
	v_mov_b32_dpp v13, v29 quad_perm:[1,0,3,2] row_mask:0xf bank_mask:0xf
	v_mov_b32_dpp v14, v30 quad_perm:[1,0,3,2] row_mask:0xf bank_mask:0xf
	v_mov_b32_dpp v15, v31 quad_perm:[1,0,3,2] row_mask:0xf bank_mask:0xf
	v_perm_b32 v16, v16, v0, v80
	v_perm_b32 v17, v17, v1, v80
	v_perm_b32 v18, v18, v2, v80
	v_perm_b32 v19, v19, v3, v80
	v_perm_b32 v20, v20, v4, v80
	v_perm_b32 v21, v21, v5, v80
	v_perm_b32 v22, v22, v6, v80
	v_perm_b32 v23, v23, v7, v80
	v_perm_b32 v24, v24, v8, v80
	v_perm_b32 v25, v25, v9, v80
	v_perm_b32 v26, v26, v10, v80
	v_perm_b32 v27, v27, v11, v80
	v_perm_b32 v28, v28, v12, v80
	v_perm_b32 v29, v29, v13, v80
	v_perm_b32 v30, v30, v14, v80
	v_perm_b32 v31, v31, v15, v80
	global_store_dword v[82:83], v16, off
	global_store_dword v[82:83], v17, off offset:256
	global_store_dword v[82:83], v18, off offset:512
	global_store_dword v[82:83], v19, off offset:768
	global_store_dword v[82:83], v20, off offset:2048
	global_store_dword v[82:83], v21, off offset:2304
	global_store_dword v[82:83], v22, off offset:2560
	global_store_dword v[82:83], v23, off offset:2816
	global_store_dword v[84:85], v24, off
	global_store_dword v[84:85], v25, off offset:256
	global_store_dword v[84:85], v26, off offset:512
	global_store_dword v[84:85], v27, off offset:768
	global_store_dword v[84:85], v28, off offset:2048
	global_store_dword v[84:85], v29, off offset:2304
	global_store_dword v[84:85], v30, off offset:2560
	global_store_dword v[84:85], v31, off offset:2816
